# prologue weight-transpose read-out (gate/up + down variants): 16 LDS reads issued together, packed gain multiply
# speedup vs baseline: 1.0224x; 1.0036x over previous
; #define LAS __attribute__((address_space(3)))
; __device__ __forceinline__ unsigned cvt_pk_bf16(float lo, float hi) { unsigned r; asm volatile("v_cvt_pk_bf16_f32 %0, %1, %2" : "=v"(r) : "v"(lo), "v"(hi)); return r; }
; __device__ __forceinline__ void transpose_item(const float* W, int N, int k0, int n0, bf16_t* WT, size_t ldk, int drow0, LAS float* scr, int lane, const float* gk = nullptr) {
;     ...
;     f32x4 ga = (f32x4){1.f, 1.f, 1.f, 1.f}, gb = ga;
;     if (gk) { ga = *(const f32x4*)(gk + k0 + 8 * c); gb = *(const f32x4*)(gk + k0 + 8 * c + 4); }
; #pragma unroll
;     for (int j = 0; j < 4; ++j) { const int n = (lane >> 3) + 8 * j; const LAS float* s = scr + (8 * c) * 33 + n;
;         u32x4 o; o.x = cvt_pk_bf16(s[0 * 33] * ga.x, s[1 * 33] * ga.y); o.y = cvt_pk_bf16(s[2 * 33] * ga.z, s[3 * 33] * ga.w); o.z = cvt_pk_bf16(s[4 * 33] * gb.x, s[5 * 33] * gb.y); o.w = cvt_pk_bf16(s[6 * 33] * gb.z, s[7 * 33] * gb.w);
;         *(u32x4*)(WT + (size_t)(drow0 + n) * ldk + k0 + 8 * c) = o; }
.LBB0_4:
	ds_read2_b32 v[170:171], v49 offset1:33
	ds_read2_b32 v[172:173], v49 offset0:66 offset1:99
	ds_read2_b32 v[174:175], v49 offset0:132 offset1:165
	ds_read2_b32 v[176:177], v49 offset0:198 offset1:231
	ds_read2_b32 v[178:179], v49 offset0:8 offset1:41
	ds_read2_b32 v[180:181], v49 offset0:74 offset1:107
	ds_read2_b32 v[182:183], v49 offset0:140 offset1:173
	ds_read2_b32 v[184:185], v49 offset0:206 offset1:239
	ds_read2_b32 v[186:187], v49 offset0:16 offset1:49
	ds_read2_b32 v[188:189], v49 offset0:82 offset1:115
	ds_read2_b32 v[190:191], v49 offset0:148 offset1:181
	ds_read2_b32 v[192:193], v49 offset0:214 offset1:247
	ds_read2_b32 v[194:195], v49 offset0:24 offset1:57
	ds_read2_b32 v[196:197], v49 offset0:90 offset1:123
	ds_read2_b32 v[198:199], v49 offset0:156 offset1:189
	ds_read2_b32 v[200:201], v49 offset0:222 offset1:255
	s_and_b64 s[8:9], s[14:15], exec
	s_cselect_b32 s8, 0, 0x80
	s_add_u32 s11, s24, s33
	s_addc_u32 s4, s25, s4
	s_lshl_b32 s9, s34, 6
	s_and_b32 s10, s10, 0x60
	s_and_b32 s9, s9, 0xffffff00
	s_or_b32 s8, s10, s8
	s_or_b32 s10, s8, s9
	s_lshl_b64 s[8:9], s[12:13], 1
	s_add_u32 s8, s11, s8
	s_addc_u32 s9, s4, s9
	v_mov_b32_e32 v17, v13
	v_lshl_add_u64 v[70:71], s[8:9], 0, v[16:17]
	s_waitcnt vmcnt(0) lgkmcnt(0)
	v_or_b32_e32 v210, s10, v48
	v_ashrrev_i32_e32 v211, 31, v210
	v_lshlrev_b64 v[210:211], 12, v[210:211]
	v_lshl_add_u64 v[210:211], v[70:71], 0, v[210:211]
	v_pk_mul_f32 v[170:171], v[6:7], v[170:171]
	v_pk_mul_f32 v[172:173], v[8:9], v[172:173]
	v_pk_mul_f32 v[174:175], v[2:3], v[174:175]
	v_pk_mul_f32 v[176:177], v[4:5], v[176:177]
	v_cvt_pk_bf16_f32 v202, v170, v171
	v_cvt_pk_bf16_f32 v203, v172, v173
	v_cvt_pk_bf16_f32 v204, v174, v175
	v_cvt_pk_bf16_f32 v205, v176, v177
	global_store_dwordx4 v[210:211], v[202:205], off
	v_or_b32_e32 v212, s10, v50
	v_ashrrev_i32_e32 v213, 31, v212
	v_lshlrev_b64 v[212:213], 12, v[212:213]
	v_lshl_add_u64 v[212:213], v[70:71], 0, v[212:213]
	v_pk_mul_f32 v[178:179], v[6:7], v[178:179]
	v_pk_mul_f32 v[180:181], v[8:9], v[180:181]
	v_pk_mul_f32 v[182:183], v[2:3], v[182:183]
	v_pk_mul_f32 v[184:185], v[4:5], v[184:185]
	v_cvt_pk_bf16_f32 v206, v178, v179
	v_cvt_pk_bf16_f32 v207, v180, v181
	v_cvt_pk_bf16_f32 v208, v182, v183
	v_cvt_pk_bf16_f32 v209, v184, v185
	global_store_dwordx4 v[212:213], v[206:209], off
	v_or_b32_e32 v214, s10, v51
	v_ashrrev_i32_e32 v215, 31, v214
	v_lshlrev_b64 v[214:215], 12, v[214:215]
	v_lshl_add_u64 v[214:215], v[70:71], 0, v[214:215]
	v_pk_mul_f32 v[186:187], v[6:7], v[186:187]
	v_pk_mul_f32 v[188:189], v[8:9], v[188:189]
	v_pk_mul_f32 v[190:191], v[2:3], v[190:191]
	v_pk_mul_f32 v[192:193], v[4:5], v[192:193]
	v_cvt_pk_bf16_f32 v202, v186, v187
	v_cvt_pk_bf16_f32 v203, v188, v189
	v_cvt_pk_bf16_f32 v204, v190, v191
	v_cvt_pk_bf16_f32 v205, v192, v193
	global_store_dwordx4 v[214:215], v[202:205], off
	v_or_b32_e32 v216, s10, v52
	v_ashrrev_i32_e32 v217, 31, v216
	v_lshlrev_b64 v[216:217], 12, v[216:217]
	v_lshl_add_u64 v[216:217], v[70:71], 0, v[216:217]
	v_pk_mul_f32 v[194:195], v[6:7], v[194:195]
	v_pk_mul_f32 v[196:197], v[8:9], v[196:197]
	v_pk_mul_f32 v[198:199], v[2:3], v[198:199]
	v_pk_mul_f32 v[200:201], v[4:5], v[200:201]
	v_cvt_pk_bf16_f32 v206, v194, v195
	v_cvt_pk_bf16_f32 v207, v196, v197
	v_cvt_pk_bf16_f32 v208, v198, v199
	v_cvt_pk_bf16_f32 v209, v200, v201
	global_store_dwordx4 v[216:217], v[206:209], off

; #define LAS __attribute__((address_space(3)))
; __device__ __forceinline__ void transpose_item(const float* W, int N, int k0, int n0, bf16_t* WT, size_t ldk, int drow0, LAS float* scr, int lane, const float* gk = nullptr) {
; #pragma unroll
;     for (int i = 0; i < 32; ++i) { const int kk = 2 * i + (lane >> 5); scr[kk * 33 + (lane & 31)] = __builtin_nontemporal_load(W + (size_t)(k0 + kk) * N + n0 + (lane & 31)); }
; __device__ __forceinline__ void phase_prologue(Frame& F, const Params& p) {
;     ...
;             const int l = r / I_L; r -= l * I_L; const int m = r / I_FF, q = r - m * I_FF;
;             if (m < 2) { const int kb = q / 176, nb = q - kb * 176, n0 = nb * 32;
;                 transpose_item((m ? p.in[16] : p.in[15]) + (size_t)l * D * FF, FF, kb * 64, n0, (bf16_t*)(F.ws + WS_WGU + l * SZ_WGU), D, 256 * (n0 >> 7) + (n0 & 127) + (m ? 128 : 0), scr, F.lane, p.in[7] + (size_t)l * D); }
;             else { const int kb = q / 64, nb = q - kb * 64;
;                 transpose_item(p.in[17] + (size_t)l * FF * D, D, kb * 64, nb * 32, (bf16_t*)(F.ws + WS_WD + l * SZ_WD), FF, nb * 32, scr, F.lane); }
.LBB0_15:
	s_andn2_b64 vcc, exec, s[8:9]
	s_cbranch_vccnz .LBB0_5
	s_mul_hi_i32 s4, s14, 0x3e0f83e1
	s_lshr_b32 s8, s4, 31
	s_ashr_i32 s4, s4, 12
	s_add_i32 s8, s4, s8
	s_mul_i32 s4, s8, 0xffffbe00
	s_add_i32 s9, s26, s4
	s_add_i32 s4, s9, 0x12c00
	s_mul_hi_i32 s10, s4, 0x2e8ba2e9
	s_lshr_b32 s11, s10, 31
	s_ashr_i32 s10, s10, 10
	s_add_i32 s10, s10, s11
	s_mulk_i32 s10, 0x1600
	s_sub_i32 s12, s4, s10
	s_mov_b64 s[10:11], -1
	s_cmpk_gt_i32 s4, 0x2bff
	s_mul_hi_i32 s4, s8, 0x2c00000
	s_mul_i32 s33, s8, 0x2c00000
	s_cbranch_scc0 .LBB0_18
	s_and_b32 s11, s12, 0x1fc0
	v_or_b32_e32 v17, s11, v19
	v_lshlrev_b32_e32 v64, 13, v17
	v_or_b32_e32 v17, s11, v20
	v_lshlrev_b32_e32 v66, 13, v17
	v_or_b32_e32 v17, s11, v21
	v_lshlrev_b32_e32 v68, 13, v17
	v_or_b32_e32 v17, s11, v22
	v_lshlrev_b32_e32 v70, 13, v17
	v_or_b32_e32 v17, s11, v23
	v_lshlrev_b32_e32 v72, 13, v17
	v_or_b32_e32 v17, s11, v24
	v_lshlrev_b32_e32 v74, 13, v17
	v_or_b32_e32 v17, s11, v25
	v_lshlrev_b32_e32 v76, 13, v17
	v_or_b32_e32 v17, s11, v26
	v_lshlrev_b32_e32 v78, 13, v17
	v_or_b32_e32 v17, s11, v27
	v_lshlrev_b32_e32 v80, 13, v17
	v_or_b32_e32 v17, s11, v28
	v_lshlrev_b32_e32 v82, 13, v17
	v_or_b32_e32 v17, s11, v29
	v_lshlrev_b32_e32 v84, 13, v17
	v_or_b32_e32 v17, s11, v30
	v_lshlrev_b32_e32 v86, 13, v17
	v_or_b32_e32 v17, s11, v31
	v_lshlrev_b32_e32 v88, 13, v17
	v_or_b32_e32 v17, s11, v32
	v_lshlrev_b32_e32 v90, 13, v17
	v_or_b32_e32 v17, s11, v33
	v_lshlrev_b32_e32 v92, 13, v17
	v_or_b32_e32 v17, s11, v34
	v_lshlrev_b32_e32 v94, 13, v17
	v_or_b32_e32 v17, s11, v35
	v_lshlrev_b32_e32 v96, 13, v17
	v_or_b32_e32 v17, s11, v36
	v_lshlrev_b32_e32 v98, 13, v17
	v_or_b32_e32 v17, s11, v37
	v_lshlrev_b32_e32 v100, 13, v17
	v_or_b32_e32 v17, s11, v38
	v_lshlrev_b32_e32 v102, 13, v17
	v_or_b32_e32 v17, s11, v39
	v_lshlrev_b32_e32 v104, 13, v17
	v_or_b32_e32 v17, s11, v40
	s_add_u32 s15, s74, s33
	v_lshlrev_b32_e32 v106, 13, v17
	v_or_b32_e32 v17, s11, v41
	s_addc_u32 s35, s75, s4
	s_lshl_b32 s10, s12, 5
	v_lshlrev_b32_e32 v108, 13, v17
	v_or_b32_e32 v17, s11, v42
	s_and_b32 s10, s10, 0x7e0
	s_mul_i32 s13, s8, 0x1600000
	v_lshlrev_b32_e32 v110, 13, v17
	v_or_b32_e32 v17, s11, v43
	s_mul_hi_i32 s14, s8, 0x1600000
	s_add_u32 s13, s22, s13
	v_lshlrev_b32_e32 v112, 13, v17
	v_or_b32_e32 v17, s11, v44
	s_addc_u32 s14, s23, s14
	s_lshl_b32 s34, s10, 2
	v_lshlrev_b32_e32 v114, 13, v17
	v_or_b32_e32 v17, s11, v45
	s_add_u32 s34, s15, s34
	v_lshlrev_b32_e32 v116, 13, v17
	v_or_b32_e32 v17, s11, v46
	s_addc_u32 s35, s35, 0
	v_or_b32_e32 v4, s11, v11
	v_or_b32_e32 v6, s11, v15
	v_or_b32_e32 v8, s11, v18
	v_lshlrev_b32_e32 v118, 13, v17
	v_or_b32_e32 v17, s11, v47
	v_lshl_add_u64 v[2:3], s[34:35], 0, v[12:13]
	v_lshlrev_b32_e32 v4, 13, v4
	v_mov_b32_e32 v5, v13
	v_lshlrev_b32_e32 v6, 13, v6
	v_mov_b32_e32 v7, v13
	v_lshlrev_b32_e32 v8, 13, v8
	v_mov_b32_e32 v9, v13
	v_mov_b32_e32 v65, v13
	v_mov_b32_e32 v67, v13
	v_mov_b32_e32 v69, v13
	v_mov_b32_e32 v71, v13
	v_mov_b32_e32 v73, v13
	v_mov_b32_e32 v75, v13
	v_mov_b32_e32 v77, v13
	v_mov_b32_e32 v79, v13
	v_mov_b32_e32 v81, v13
	v_mov_b32_e32 v83, v13
	v_mov_b32_e32 v85, v13
	v_mov_b32_e32 v87, v13
	v_mov_b32_e32 v89, v13
	v_mov_b32_e32 v91, v13
	v_mov_b32_e32 v93, v13
	v_mov_b32_e32 v95, v13
	v_mov_b32_e32 v97, v13
	v_mov_b32_e32 v99, v13
	v_mov_b32_e32 v101, v13
	v_mov_b32_e32 v103, v13
	v_mov_b32_e32 v105, v13
	v_mov_b32_e32 v107, v13
	v_mov_b32_e32 v109, v13
	v_mov_b32_e32 v111, v13
	v_mov_b32_e32 v113, v13
	v_mov_b32_e32 v115, v13
	v_mov_b32_e32 v117, v13
	v_mov_b32_e32 v119, v13
	v_lshlrev_b32_e32 v120, 13, v17
	v_mov_b32_e32 v121, v13
	v_lshl_add_u64 v[4:5], v[2:3], 0, v[4:5]
	v_lshl_add_u64 v[6:7], v[2:3], 0, v[6:7]
	v_lshl_add_u64 v[8:9], v[2:3], 0, v[8:9]
	v_lshl_add_u64 v[64:65], v[2:3], 0, v[64:65]
	v_lshl_add_u64 v[66:67], v[2:3], 0, v[66:67]
	v_lshl_add_u64 v[68:69], v[2:3], 0, v[68:69]
	v_lshl_add_u64 v[70:71], v[2:3], 0, v[70:71]
	v_lshl_add_u64 v[72:73], v[2:3], 0, v[72:73]
	v_lshl_add_u64 v[74:75], v[2:3], 0, v[74:75]
	v_lshl_add_u64 v[76:77], v[2:3], 0, v[76:77]
	v_lshl_add_u64 v[78:79], v[2:3], 0, v[78:79]
	v_lshl_add_u64 v[80:81], v[2:3], 0, v[80:81]
	v_lshl_add_u64 v[82:83], v[2:3], 0, v[82:83]
	v_lshl_add_u64 v[84:85], v[2:3], 0, v[84:85]
	v_lshl_add_u64 v[86:87], v[2:3], 0, v[86:87]
	v_lshl_add_u64 v[88:89], v[2:3], 0, v[88:89]
	v_lshl_add_u64 v[90:91], v[2:3], 0, v[90:91]
	v_lshl_add_u64 v[92:93], v[2:3], 0, v[92:93]
	v_lshl_add_u64 v[94:95], v[2:3], 0, v[94:95]
	v_lshl_add_u64 v[96:97], v[2:3], 0, v[96:97]
	v_lshl_add_u64 v[98:99], v[2:3], 0, v[98:99]
	v_lshl_add_u64 v[100:101], v[2:3], 0, v[100:101]
	v_lshl_add_u64 v[102:103], v[2:3], 0, v[102:103]
	v_lshl_add_u64 v[104:105], v[2:3], 0, v[104:105]
	v_lshl_add_u64 v[106:107], v[2:3], 0, v[106:107]
	v_lshl_add_u64 v[108:109], v[2:3], 0, v[108:109]
	v_lshl_add_u64 v[110:111], v[2:3], 0, v[110:111]
	v_lshl_add_u64 v[112:113], v[2:3], 0, v[112:113]
	v_lshl_add_u64 v[114:115], v[2:3], 0, v[114:115]
	v_lshl_add_u64 v[116:117], v[2:3], 0, v[116:117]
	v_lshl_add_u64 v[118:119], v[2:3], 0, v[118:119]
	v_lshl_add_u64 v[2:3], v[2:3], 0, v[120:121]
	global_load_dword v4, v[4:5], off nt
	s_nop 0
	global_load_dword v5, v[6:7], off nt
	s_nop 0
	global_load_dword v6, v[8:9], off nt
	global_load_dword v7, v[64:65], off nt
	s_nop 0
	global_load_dword v8, v[66:67], off nt
	global_load_dword v9, v[68:69], off nt
	global_load_dword v17, v[70:71], off nt
	global_load_dword v63, v[72:73], off nt
	global_load_dword v64, v[74:75], off nt
	global_load_dword v65, v[76:77], off nt
	global_load_dword v66, v[78:79], off nt
	global_load_dword v67, v[80:81], off nt
	global_load_dword v68, v[82:83], off nt
	global_load_dword v69, v[84:85], off nt
	global_load_dword v70, v[86:87], off nt
	global_load_dword v71, v[88:89], off nt
	global_load_dword v72, v[90:91], off nt
	global_load_dword v73, v[92:93], off nt
	global_load_dword v74, v[94:95], off nt
	global_load_dword v75, v[96:97], off nt
	global_load_dword v76, v[98:99], off nt
	global_load_dword v77, v[100:101], off nt
	global_load_dword v78, v[102:103], off nt
	global_load_dword v79, v[104:105], off nt
	global_load_dword v80, v[106:107], off nt
	global_load_dword v81, v[108:109], off nt
	global_load_dword v82, v[110:111], off nt
	global_load_dword v83, v[112:113], off nt
	global_load_dword v84, v[114:115], off nt
	global_load_dword v85, v[116:117], off nt
	global_load_dword v86, v[118:119], off nt
	s_nop 0
	global_load_dword v2, v[2:3], off nt
	s_waitcnt vmcnt(30)
; #define LAS __attribute__((address_space(3)))
; __device__ __forceinline__ unsigned cvt_pk_bf16(float lo, float hi) { unsigned r; asm volatile("v_cvt_pk_bf16_f32 %0, %1, %2" : "=v"(r) : "v"(lo), "v"(hi)); return r; }
; #define LDS_WAIT() asm volatile("s_waitcnt lgkmcnt(0)" ::: "memory")
; __device__ __forceinline__ void transpose_item(const float* W, int N, int k0, int n0, bf16_t* WT, size_t ldk, int drow0, LAS float* scr, int lane, const float* gk = nullptr) {
;     ...
;     for (int i = 0; i < 32; ++i) { const int kk = 2 * i + (lane >> 5); scr[kk * 33 + (lane & 31)] = __builtin_nontemporal_load(W + (size_t)(k0 + kk) * N + n0 + (lane & 31)); }
;     LDS_WAIT();
;     const int c = lane & 7;
;     f32x4 ga = (f32x4){1.f, 1.f, 1.f, 1.f}, gb = ga;
;     if (gk) { ga = *(const f32x4*)(gk + k0 + 8 * c); gb = *(const f32x4*)(gk + k0 + 8 * c + 4); }
; #pragma unroll
;     for (int j = 0; j < 4; ++j) { const int n = (lane >> 3) + 8 * j; const LAS float* s = scr + (8 * c) * 33 + n;
;         u32x4 o; o.x = cvt_pk_bf16(s[0 * 33] * ga.x, s[1 * 33] * ga.y); o.y = cvt_pk_bf16(s[2 * 33] * ga.z, s[3 * 33] * ga.w); o.z = cvt_pk_bf16(s[4 * 33] * gb.x, s[5 * 33] * gb.y); o.w = cvt_pk_bf16(s[6 * 33] * gb.z, s[7 * 33] * gb.w);
;         *(u32x4*)(WT + (size_t)(drow0 + n) * ldk + k0 + 8 * c) = o; }
;     LDS_WAIT();
	ds_write2_b32 v53, v4, v5 offset1:66
	s_waitcnt vmcnt(28)
	ds_write2_b32 v53, v6, v7 offset0:132 offset1:198
	s_waitcnt vmcnt(26)
	ds_write2_b32 v58, v8, v9 offset0:8 offset1:74
	s_waitcnt vmcnt(24)
	ds_write2_b32 v54, v17, v63 offset1:66
	s_waitcnt vmcnt(22)
	ds_write2_b32 v54, v64, v65 offset0:132 offset1:198
	s_waitcnt vmcnt(20)
	ds_write2_b32 v59, v66, v67 offset0:8 offset1:74
	s_waitcnt vmcnt(18)
	ds_write2_b32 v55, v68, v69 offset1:66
	s_waitcnt vmcnt(16)
	ds_write2_b32 v55, v70, v71 offset0:132 offset1:198
	s_waitcnt vmcnt(14)
	ds_write2_b32 v60, v72, v73 offset0:8 offset1:74
	s_waitcnt vmcnt(12)
	ds_write2_b32 v56, v74, v75 offset1:66
	s_waitcnt vmcnt(10)
	ds_write2_b32 v56, v76, v77 offset0:132 offset1:198
	s_waitcnt vmcnt(8)
	ds_write2_b32 v61, v78, v79 offset0:8 offset1:74
	s_waitcnt vmcnt(6)
	ds_write2_b32 v57, v80, v81 offset1:66
	s_waitcnt vmcnt(4)
	ds_write2_b32 v57, v82, v83 offset0:132 offset1:198
	s_waitcnt vmcnt(2)
	ds_write2_b32 v62, v84, v85 offset0:8 offset1:74
	s_waitcnt vmcnt(0)
	ds_write2_b32 v62, v86, v2 offset0:140 offset1:206
	s_lshl_b32 s11, s11, 1
	s_waitcnt lgkmcnt(0)
	s_add_u32 s34, s13, s11
	s_addc_u32 s35, s14, 0
	ds_read2_b32 v[170:171], v49 offset1:33
	ds_read2_b32 v[172:173], v49 offset0:66 offset1:99
	ds_read2_b32 v[174:175], v49 offset0:132 offset1:165
	ds_read2_b32 v[176:177], v49 offset0:198 offset1:231
	ds_read2_b32 v[178:179], v49 offset0:8 offset1:41
	ds_read2_b32 v[180:181], v49 offset0:74 offset1:107
	ds_read2_b32 v[182:183], v49 offset0:140 offset1:173
	ds_read2_b32 v[184:185], v49 offset0:206 offset1:239
	ds_read2_b32 v[186:187], v49 offset0:16 offset1:49
	ds_read2_b32 v[188:189], v49 offset0:82 offset1:115
	ds_read2_b32 v[190:191], v49 offset0:148 offset1:181
	ds_read2_b32 v[192:193], v49 offset0:214 offset1:247
	ds_read2_b32 v[194:195], v49 offset0:24 offset1:57
	ds_read2_b32 v[196:197], v49 offset0:90 offset1:123
	ds_read2_b32 v[198:199], v49 offset0:156 offset1:189
	ds_read2_b32 v[200:201], v49 offset0:222 offset1:255
	v_mov_b32_e32 v17, v13
	v_lshl_add_u64 v[8:9], s[34:35], 0, v[16:17]
	v_or_b32_e32 v210, s10, v48
	v_mul_u32_u24_e32 v210, 0x2c00, v210
	v_mov_b32_e32 v211, v13
	v_lshl_add_u64 v[210:211], v[8:9], 0, v[210:211]
	v_or_b32_e32 v212, s10, v50
	v_mul_u32_u24_e32 v212, 0x2c00, v212
	v_mov_b32_e32 v213, v13
	v_lshl_add_u64 v[212:213], v[8:9], 0, v[212:213]
	v_or_b32_e32 v214, s10, v51
	v_mul_u32_u24_e32 v214, 0x2c00, v214
	v_mov_b32_e32 v215, v13
	v_lshl_add_u64 v[214:215], v[8:9], 0, v[214:215]
	v_or_b32_e32 v216, s10, v52
	v_mul_u32_u24_e32 v216, 0x2c00, v216
	v_mov_b32_e32 v217, v13
	v_lshl_add_u64 v[216:217], v[8:9], 0, v[216:217]
	s_waitcnt lgkmcnt(0)
	v_cvt_pk_bf16_f32 v202, v170, v171
	v_cvt_pk_bf16_f32 v203, v172, v173
	v_cvt_pk_bf16_f32 v204, v174, v175
	v_cvt_pk_bf16_f32 v205, v176, v177
	global_store_dwordx4 v[210:211], v[202:205], off
	v_cvt_pk_bf16_f32 v206, v178, v179
	v_cvt_pk_bf16_f32 v207, v180, v181
	v_cvt_pk_bf16_f32 v208, v182, v183
	v_cvt_pk_bf16_f32 v209, v184, v185
	global_store_dwordx4 v[212:213], v[206:209], off
	v_cvt_pk_bf16_f32 v202, v186, v187
	v_cvt_pk_bf16_f32 v203, v188, v189
	v_cvt_pk_bf16_f32 v204, v190, v191
	v_cvt_pk_bf16_f32 v205, v192, v193
	global_store_dwordx4 v[214:215], v[202:205], off
	v_cvt_pk_bf16_f32 v206, v194, v195
	v_cvt_pk_bf16_f32 v207, v196, v197
	v_cvt_pk_bf16_f32 v208, v198, v199
	v_cvt_pk_bf16_f32 v209, v200, v201
	global_store_dwordx4 v[216:217], v[206:209], off
	s_mov_b64 s[10:11], 0
